# layer-1 in/out-proj and GLU weight transposes moved from the layer-0 down-proj phase's helper workgroups to the idle workgroups of the layer-0 out-proj phase (pipelined 16-byte-load loop)
# baseline (speedup 1.0000x reference)
.Ltq_entry:
	s_cmp_lt_u32 s2, 0xc0
	s_cbranch_scc1 .Ltq_done
	v_mov_b32_e32 v1, 0
	global_load_dwordx2 v[20:21], v1, s[96:97] offset:152 sc0
	global_load_dwordx2 v[22:23], v1, s[96:97] offset:248 sc0
	global_load_dwordx2 v[24:25], v1, s[96:97] offset:232 sc0
	v_mbcnt_lo_u32_b32 v19, -1, 0
	v_mbcnt_hi_u32_b32 v19, -1, v19
	v_lshrrev_b32_e32 v3, 3, v19
	v_and_b32_e32 v2, 7, v19
	v_lshlrev_b32_e32 v4, 4, v2
	s_lshl_b32 s4, s94, 14
	v_mul_u32_u24_e32 v5, 33, v3
	v_lshl_add_u32 v5, v2, 2, v5
	v_lshl_add_u32 v5, v5, 2, s4
	v_mul_u32_u24_e32 v6, 0x108, v2
	v_add_u32_e32 v6, v6, v3
	v_lshl_add_u32 v6, v6, 2, s4
	s_waitcnt vmcnt(0)
	v_readfirstlane_b32 s24, v20
	v_readfirstlane_b32 s25, v21
	v_readfirstlane_b32 s26, v22
	v_readfirstlane_b32 s27, v23
	v_readfirstlane_b32 s28, v24
	v_readfirstlane_b32 s29, v25
	s_sub_i32 s0, s2, 0xc0
	s_lshl_b32 s0, s0, 3
	s_add_i32 s0, s0, s94
	s_movk_i32 s1, 0x200
	s_movk_i32 s9, 0x680
	s_cmp_lt_u32 s0, s9
	s_cbranch_scc0 .Ltq_done
	s_cmpk_lt_u32 s0, 0x400
	s_cbranch_scc0 .Ltq_c1_p
	v_mov_b32_e32 v30, s0
	v_mov_b32_e32 v24, s24
	v_mov_b32_e32 v25, s25
	v_mov_b32_e32 v26, 6
	v_mov_b32_e32 v27, 11
	s_add_u32 s4, s54, 0x1b00000
	s_addc_u32 s5, s55, 0
	v_mov_b32_e32 v28, s4
	v_mov_b32_e32 v29, s5
	s_branch .Ltq_go_p
.Ltq_c1_p:
	s_cmpk_lt_u32 s0, 0x600
	s_cbranch_scc0 .Ltq_c2_p
	s_sub_i32 s4, s0, 0x400
	v_mov_b32_e32 v30, s4
	v_mov_b32_e32 v24, s26
	v_mov_b32_e32 v25, s27
	v_mov_b32_e32 v26, 5
	v_mov_b32_e32 v27, 11
	s_add_u32 s4, s54, 0x1f00000
	s_addc_u32 s5, s55, 0
	v_mov_b32_e32 v28, s4
	v_mov_b32_e32 v29, s5
	s_branch .Ltq_go_p
.Ltq_c2_p:
	s_sub_i32 s4, s0, 0x600
	v_mov_b32_e32 v30, s4
	v_mov_b32_e32 v24, s28
	v_mov_b32_e32 v25, s29
	v_mov_b32_e32 v26, 4
	v_mov_b32_e32 v27, 10
	s_add_u32 s4, s54, 0x3100000
	s_addc_u32 s5, s55, 0
	v_mov_b32_e32 v28, s4
	v_mov_b32_e32 v29, s5
.Ltq_go_p:
	v_lshrrev_b32_e32 v31, v26, v30
	v_lshlrev_b32_e32 v20, v26, v31
	v_sub_u32_e32 v20, v30, v20
	v_add_u32_e32 v21, 13, v26
	v_lshlrev_b32_e32 v21, v21, v31
	v_lshl_add_u32 v21, v20, 7, v21
	v_add_u32_e32 v22, 7, v26
	v_lshlrev_b32_e32 v23, v22, v3
	v_add3_u32 v21, v21, v23, v4
	v_add_co_u32_e32 v20, vcc, v24, v21
	s_nop 1
	v_addc_co_u32_e32 v21, vcc, 0, v25, vcc
	v_add_u32_e32 v22, 3, v22
	v_lshlrev_b32_e64 v22, v22, 1
	v_mov_b32_e32 v23, 0
	global_load_dwordx4 v[32:35], v[20:21], off
	v_lshl_add_u64 v[20:21], v[20:21], 0, v[22:23]
	global_load_dwordx4 v[36:39], v[20:21], off
	v_lshl_add_u64 v[20:21], v[20:21], 0, v[22:23]
	global_load_dwordx4 v[40:43], v[20:21], off
	v_lshl_add_u64 v[20:21], v[20:21], 0, v[22:23]
	global_load_dwordx4 v[44:47], v[20:21], off
	v_lshl_add_u64 v[20:21], v[20:21], 0, v[22:23]
	global_load_dwordx4 v[48:51], v[20:21], off
	v_lshl_add_u64 v[20:21], v[20:21], 0, v[22:23]
	global_load_dwordx4 v[52:55], v[20:21], off
	v_lshl_add_u64 v[20:21], v[20:21], 0, v[22:23]
	global_load_dwordx4 v[56:59], v[20:21], off
	v_lshl_add_u64 v[20:21], v[20:21], 0, v[22:23]
	global_load_dwordx4 v[60:63], v[20:21], off
	v_lshlrev_b32_e32 v20, v26, v31
	v_sub_u32_e32 v20, v30, v20
	v_lshl_add_u32 v20, v20, 5, v3
	v_lshlrev_b32_e32 v20, v27, v20
	v_lshl_add_u32 v20, v31, 7, v20
	v_add_u32_e32 v20, v20, v4
	v_add_co_u32_e32 v10, vcc, v28, v20
	s_nop 1
	v_addc_co_u32_e32 v11, vcc, 0, v29, vcc
	v_add_u32_e32 v21, 3, v27
	v_lshlrev_b32_e64 v12, v21, 1
	v_mov_b32_e32 v13, 0
	global_load_dword v7, v1, s[96:97] offset:4
	global_load_dword v8, v1, s[96:97] offset:8
	global_load_dword v9, v1, s[96:97] offset:12
	global_load_dword v18, v1, s[96:97] offset:16
.Ltq_loop:
	s_add_i32 s0, s0, s1
	s_cmp_lt_u32 s0, s9
	s_cbranch_scc0 .Ltq_last_x0
	s_cmpk_lt_u32 s0, 0x400
	s_cbranch_scc0 .Ltq_c1_x0
	v_mov_b32_e32 v30, s0
	v_mov_b32_e32 v24, s24
	v_mov_b32_e32 v25, s25
	v_mov_b32_e32 v26, 6
	v_mov_b32_e32 v27, 11
	s_add_u32 s4, s54, 0x1b00000
	s_addc_u32 s5, s55, 0
	v_mov_b32_e32 v28, s4
	v_mov_b32_e32 v29, s5
	s_branch .Ltq_go_x0

.Ltq_go_x0:
	v_lshrrev_b32_e32 v31, v26, v30
	v_lshlrev_b32_e32 v20, v26, v31
	v_sub_u32_e32 v20, v30, v20
	v_add_u32_e32 v21, 13, v26
	v_lshlrev_b32_e32 v21, v21, v31
	v_lshl_add_u32 v21, v20, 7, v21
	v_add_u32_e32 v22, 7, v26
	v_lshlrev_b32_e32 v23, v22, v3
	v_add3_u32 v21, v21, v23, v4
	v_add_co_u32_e32 v20, vcc, v24, v21
	s_nop 1
	v_addc_co_u32_e32 v21, vcc, 0, v25, vcc
	v_add_u32_e32 v22, 3, v22
	v_lshlrev_b32_e64 v22, v22, 1
	v_mov_b32_e32 v23, 0
	global_load_dwordx4 v[64:67], v[20:21], off
	v_lshl_add_u64 v[20:21], v[20:21], 0, v[22:23]
	global_load_dwordx4 v[68:71], v[20:21], off
	v_lshl_add_u64 v[20:21], v[20:21], 0, v[22:23]
	global_load_dwordx4 v[72:75], v[20:21], off
	v_lshl_add_u64 v[20:21], v[20:21], 0, v[22:23]
	global_load_dwordx4 v[76:79], v[20:21], off
	v_lshl_add_u64 v[20:21], v[20:21], 0, v[22:23]
	global_load_dwordx4 v[80:83], v[20:21], off
	v_lshl_add_u64 v[20:21], v[20:21], 0, v[22:23]
	global_load_dwordx4 v[84:87], v[20:21], off
	v_lshl_add_u64 v[20:21], v[20:21], 0, v[22:23]
	global_load_dwordx4 v[88:91], v[20:21], off
	v_lshl_add_u64 v[20:21], v[20:21], 0, v[22:23]
	global_load_dwordx4 v[92:95], v[20:21], off
	v_lshlrev_b32_e32 v20, v26, v31
	v_sub_u32_e32 v20, v30, v20
	v_lshl_add_u32 v20, v20, 5, v3
	v_lshlrev_b32_e32 v20, v27, v20
	v_lshl_add_u32 v20, v31, 7, v20
	v_add_u32_e32 v20, v20, v4
	v_add_co_u32_e32 v14, vcc, v28, v20
	s_nop 1
	v_addc_co_u32_e32 v15, vcc, 0, v29, vcc
	v_add_u32_e32 v21, 3, v27
	v_lshlrev_b32_e64 v16, v21, 1
	v_mov_b32_e32 v17, 0
	s_waitcnt vmcnt(12)
	ds_write_b32 v5, v32
	ds_write_b32 v5, v33 offset:4
	ds_write_b32 v5, v34 offset:8
	ds_write_b32 v5, v35 offset:12
	ds_write_b32 v5, v36 offset:1056
	ds_write_b32 v5, v37 offset:1060
	ds_write_b32 v5, v38 offset:1064
	ds_write_b32 v5, v39 offset:1068
	ds_write_b32 v5, v40 offset:2112
	ds_write_b32 v5, v41 offset:2116
	ds_write_b32 v5, v42 offset:2120
	ds_write_b32 v5, v43 offset:2124
	ds_write_b32 v5, v44 offset:3168
	ds_write_b32 v5, v45 offset:3172
	ds_write_b32 v5, v46 offset:3176
	ds_write_b32 v5, v47 offset:3180
	ds_write_b32 v5, v48 offset:4224
	ds_write_b32 v5, v49 offset:4228
	ds_write_b32 v5, v50 offset:4232
	ds_write_b32 v5, v51 offset:4236
	ds_write_b32 v5, v52 offset:5280
	ds_write_b32 v5, v53 offset:5284
	ds_write_b32 v5, v54 offset:5288
	ds_write_b32 v5, v55 offset:5292
	ds_write_b32 v5, v56 offset:6336
	ds_write_b32 v5, v57 offset:6340
	ds_write_b32 v5, v58 offset:6344
	ds_write_b32 v5, v59 offset:6348
	ds_write_b32 v5, v60 offset:7392
	ds_write_b32 v5, v61 offset:7396
	ds_write_b32 v5, v62 offset:7400
	ds_write_b32 v5, v63 offset:7404
	s_waitcnt lgkmcnt(0)
	ds_read2_b32 v[96:97], v6 offset0:0 offset1:33
	ds_read2_b32 v[98:99], v6 offset0:66 offset1:99
	ds_read2_b32 v[100:101], v6 offset0:132 offset1:165
	ds_read2_b32 v[102:103], v6 offset0:198 offset1:231
	ds_read2_b32 v[104:105], v6 offset0:8 offset1:41
	ds_read2_b32 v[106:107], v6 offset0:74 offset1:107
	ds_read2_b32 v[108:109], v6 offset0:140 offset1:173
	ds_read2_b32 v[110:111], v6 offset0:206 offset1:239
	ds_read2_b32 v[112:113], v6 offset0:16 offset1:49
	ds_read2_b32 v[114:115], v6 offset0:82 offset1:115
	ds_read2_b32 v[116:117], v6 offset0:148 offset1:181
	ds_read2_b32 v[118:119], v6 offset0:214 offset1:247
	ds_read2_b32 v[120:121], v6 offset0:24 offset1:57
	ds_read2_b32 v[122:123], v6 offset0:90 offset1:123
	ds_read2_b32 v[124:125], v6 offset0:156 offset1:189
	ds_read2_b32 v[126:127], v6 offset0:222 offset1:255
	s_waitcnt lgkmcnt(0)
	v_cvt_pk_bf16_f32 v128, v96, v97
	v_cvt_pk_bf16_f32 v129, v98, v99
	v_cvt_pk_bf16_f32 v130, v100, v101
	v_cvt_pk_bf16_f32 v131, v102, v103
	global_store_dwordx4 v[10:11], v[128:131], off
	v_lshl_add_u64 v[10:11], v[10:11], 0, v[12:13]
	v_cvt_pk_bf16_f32 v132, v104, v105
	v_cvt_pk_bf16_f32 v133, v106, v107
	v_cvt_pk_bf16_f32 v134, v108, v109
	v_cvt_pk_bf16_f32 v135, v110, v111
	global_store_dwordx4 v[10:11], v[132:135], off
	v_lshl_add_u64 v[10:11], v[10:11], 0, v[12:13]
	v_cvt_pk_bf16_f32 v136, v112, v113
	v_cvt_pk_bf16_f32 v137, v114, v115
	v_cvt_pk_bf16_f32 v138, v116, v117
	v_cvt_pk_bf16_f32 v139, v118, v119
	global_store_dwordx4 v[10:11], v[136:139], off
	v_lshl_add_u64 v[10:11], v[10:11], 0, v[12:13]
	v_cvt_pk_bf16_f32 v140, v120, v121
	v_cvt_pk_bf16_f32 v141, v122, v123
	v_cvt_pk_bf16_f32 v142, v124, v125
	v_cvt_pk_bf16_f32 v143, v126, v127
	global_store_dwordx4 v[10:11], v[140:143], off
	s_branch .Ltq_cont_x0

.Ltq_go_x1:
	v_lshrrev_b32_e32 v31, v26, v30
	v_lshlrev_b32_e32 v20, v26, v31
	v_sub_u32_e32 v20, v30, v20
	v_add_u32_e32 v21, 13, v26
	v_lshlrev_b32_e32 v21, v21, v31
	v_lshl_add_u32 v21, v20, 7, v21
	v_add_u32_e32 v22, 7, v26
	v_lshlrev_b32_e32 v23, v22, v3
	v_add3_u32 v21, v21, v23, v4
	v_add_co_u32_e32 v20, vcc, v24, v21
	s_nop 1
	v_addc_co_u32_e32 v21, vcc, 0, v25, vcc
	v_add_u32_e32 v22, 3, v22
	v_lshlrev_b32_e64 v22, v22, 1
	v_mov_b32_e32 v23, 0
	global_load_dwordx4 v[32:35], v[20:21], off
	v_lshl_add_u64 v[20:21], v[20:21], 0, v[22:23]
	global_load_dwordx4 v[36:39], v[20:21], off
	v_lshl_add_u64 v[20:21], v[20:21], 0, v[22:23]
	global_load_dwordx4 v[40:43], v[20:21], off
	v_lshl_add_u64 v[20:21], v[20:21], 0, v[22:23]
	global_load_dwordx4 v[44:47], v[20:21], off
	v_lshl_add_u64 v[20:21], v[20:21], 0, v[22:23]
	global_load_dwordx4 v[48:51], v[20:21], off
	v_lshl_add_u64 v[20:21], v[20:21], 0, v[22:23]
	global_load_dwordx4 v[52:55], v[20:21], off
	v_lshl_add_u64 v[20:21], v[20:21], 0, v[22:23]
	global_load_dwordx4 v[56:59], v[20:21], off
	v_lshl_add_u64 v[20:21], v[20:21], 0, v[22:23]
	global_load_dwordx4 v[60:63], v[20:21], off
	v_lshlrev_b32_e32 v20, v26, v31
	v_sub_u32_e32 v20, v30, v20
	v_lshl_add_u32 v20, v20, 5, v3
	v_lshlrev_b32_e32 v20, v27, v20
	v_lshl_add_u32 v20, v31, 7, v20
	v_add_u32_e32 v20, v20, v4
	v_add_co_u32_e32 v10, vcc, v28, v20
	s_nop 1
	v_addc_co_u32_e32 v11, vcc, 0, v29, vcc
	v_add_u32_e32 v21, 3, v27
	v_lshlrev_b32_e64 v12, v21, 1
	v_mov_b32_e32 v13, 0
	s_waitcnt vmcnt(12)
	ds_write_b32 v5, v64
	ds_write_b32 v5, v65 offset:4
	ds_write_b32 v5, v66 offset:8
	ds_write_b32 v5, v67 offset:12
	ds_write_b32 v5, v68 offset:1056
	ds_write_b32 v5, v69 offset:1060
	ds_write_b32 v5, v70 offset:1064
	ds_write_b32 v5, v71 offset:1068
	ds_write_b32 v5, v72 offset:2112
	ds_write_b32 v5, v73 offset:2116
	ds_write_b32 v5, v74 offset:2120
	ds_write_b32 v5, v75 offset:2124
	ds_write_b32 v5, v76 offset:3168
	ds_write_b32 v5, v77 offset:3172
	ds_write_b32 v5, v78 offset:3176
	ds_write_b32 v5, v79 offset:3180
	ds_write_b32 v5, v80 offset:4224
	ds_write_b32 v5, v81 offset:4228
	ds_write_b32 v5, v82 offset:4232
	ds_write_b32 v5, v83 offset:4236
	ds_write_b32 v5, v84 offset:5280
	ds_write_b32 v5, v85 offset:5284
	ds_write_b32 v5, v86 offset:5288
	ds_write_b32 v5, v87 offset:5292
	ds_write_b32 v5, v88 offset:6336
	ds_write_b32 v5, v89 offset:6340
	ds_write_b32 v5, v90 offset:6344
	ds_write_b32 v5, v91 offset:6348
	ds_write_b32 v5, v92 offset:7392
	ds_write_b32 v5, v93 offset:7396
	ds_write_b32 v5, v94 offset:7400
	ds_write_b32 v5, v95 offset:7404
	s_waitcnt lgkmcnt(0)
	ds_read2_b32 v[96:97], v6 offset0:0 offset1:33
	ds_read2_b32 v[98:99], v6 offset0:66 offset1:99
	ds_read2_b32 v[100:101], v6 offset0:132 offset1:165
	ds_read2_b32 v[102:103], v6 offset0:198 offset1:231
	ds_read2_b32 v[104:105], v6 offset0:8 offset1:41
	ds_read2_b32 v[106:107], v6 offset0:74 offset1:107
	ds_read2_b32 v[108:109], v6 offset0:140 offset1:173
	ds_read2_b32 v[110:111], v6 offset0:206 offset1:239
	ds_read2_b32 v[112:113], v6 offset0:16 offset1:49
	ds_read2_b32 v[114:115], v6 offset0:82 offset1:115
	ds_read2_b32 v[116:117], v6 offset0:148 offset1:181
	ds_read2_b32 v[118:119], v6 offset0:214 offset1:247
	ds_read2_b32 v[120:121], v6 offset0:24 offset1:57
	ds_read2_b32 v[122:123], v6 offset0:90 offset1:123
	ds_read2_b32 v[124:125], v6 offset0:156 offset1:189
	ds_read2_b32 v[126:127], v6 offset0:222 offset1:255
	s_waitcnt lgkmcnt(0)
	v_cvt_pk_bf16_f32 v128, v96, v97
	v_cvt_pk_bf16_f32 v129, v98, v99
	v_cvt_pk_bf16_f32 v130, v100, v101
	v_cvt_pk_bf16_f32 v131, v102, v103
	global_store_dwordx4 v[14:15], v[128:131], off
	v_lshl_add_u64 v[14:15], v[14:15], 0, v[16:17]
	v_cvt_pk_bf16_f32 v132, v104, v105
	v_cvt_pk_bf16_f32 v133, v106, v107
	v_cvt_pk_bf16_f32 v134, v108, v109
	v_cvt_pk_bf16_f32 v135, v110, v111
	global_store_dwordx4 v[14:15], v[132:135], off
	v_lshl_add_u64 v[14:15], v[14:15], 0, v[16:17]
	v_cvt_pk_bf16_f32 v136, v112, v113
	v_cvt_pk_bf16_f32 v137, v114, v115
	v_cvt_pk_bf16_f32 v138, v116, v117
	v_cvt_pk_bf16_f32 v139, v118, v119
	global_store_dwordx4 v[14:15], v[136:139], off
	v_lshl_add_u64 v[14:15], v[14:15], 0, v[16:17]
	v_cvt_pk_bf16_f32 v140, v120, v121
	v_cvt_pk_bf16_f32 v141, v122, v123
	v_cvt_pk_bf16_f32 v142, v124, v125
	v_cvt_pk_bf16_f32 v143, v126, v127
	global_store_dwordx4 v[14:15], v[140:143], off
	s_branch .Ltq_loop

.LBB0_541:
	s_cmpk_lt_i32 s2, 0xc0
	s_cbranch_scc1 .LBB0_572
	v_mov_b32_e32 v1, 0
	global_load_dwordx2 v[2:3], v1, s[96:97] offset:96 sc0
	global_load_dwordx2 v[2:3], v1, s[96:97] offset:104 sc0
	global_load_dwordx2 v[2:3], v1, s[96:97] offset:152 sc0
	global_load_dwordx2 v[4:5], v1, s[96:97] offset:248 sc0
	global_load_dwordx2 v[6:7], v1, s[96:97] offset:232 sc0
	s_add_i32 s3, s2, 0xffffff40
	s_lshl_b32 s0, s3, 3
	s_add_i32 s10, s94, s0
	v_readlane_b32 s28, v246, 8
	s_cmpk_gt_i32 s10, 0x67f
	v_readlane_b32 s29, v246, 9
	v_mbcnt_lo_u32_b32 v14, -1, 0
	v_mbcnt_hi_u32_b32 v14, -1, v14
	s_waitcnt vmcnt(2)
	v_readfirstlane_b32 s5, v3
	v_readfirstlane_b32 s4, v2
	s_waitcnt vmcnt(1)
	v_readfirstlane_b32 s7, v5
	v_readfirstlane_b32 s6, v4
	s_waitcnt vmcnt(0)
	v_readfirstlane_b32 s9, v7
	v_readfirstlane_b32 s8, v6
	s_branch .LBB0_553
	v_lshlrev_b32_e32 v0, 2, v14
	v_and_b32_e32 v0, 0x7c, v0
	s_lshl_b32 s0, s94, 14
	v_ashrrev_i32_e32 v15, 5, v14
	v_lshl_add_u64 v[2:3], s[8:9], 0, v[0:1]
	s_movk_i32 s8, 0x84
	s_add_i32 s0, s0, 0
	v_mul_lo_u32 v4, v15, s8
	v_add3_u32 v16, s0, v0, v4
	v_lshlrev_b32_e32 v4, 3, v14
	v_ashrrev_i32_e32 v17, 3, v14
	v_and_b32_e32 v4, 56, v4
	v_mul_u32_u24_e32 v6, 0x84, v4
	v_lshlrev_b32_e32 v7, 2, v17
	v_lshlrev_b32_e32 v12, 1, v4
	v_mov_b32_e32 v13, v1
	v_add3_u32 v18, s0, v6, v7
	s_lshl_b32 s0, s10, 1
	s_mov_b32 s1, 0
	v_lshl_add_u64 v[4:5], s[36:37], 0, v[12:13]
	v_add_u32_e32 v19, 8, v17
	v_add_u32_e32 v20, 16, v17
	v_add_u32_e32 v21, 24, v17
	v_lshl_add_u64 v[6:7], s[6:7], 0, v[0:1]
	v_lshl_add_u64 v[8:9], s[26:27], 0, v[12:13]
	v_lshl_add_u64 v[10:11], s[4:5], 0, v[0:1]
	v_lshl_add_u64 v[12:13], s[20:21], 0, v[12:13]
	s_lshl_b32 s8, s10, 5
	s_lshl_b32 s9, s10, 2
	s_add_i32 s11, s0, 0x1f800
	v_add_u32_e32 v0, 0x400, v16
	v_add_u32_e32 v22, 0x800, v16
	v_add_u32_e32 v23, 0xc00, v16
	v_add_u32_e32 v24, 0x1000, v16
	v_add_u32_e32 v25, 0x1400, v16
	v_add_u32_e32 v26, 0x1800, v16
	v_add_u32_e32 v27, 0x1c00, v16
	s_branch .LBB0_545
